# static s_setprio 1 for waves 4-7 in the attention main loop (on top of one-barrier loop)
# speedup vs baseline: 1.0138x; 1.0102x over previous
; DI unsigned cvtpk(float lo, float hi) { unsigned r; asm volatile("v_cvt_pk_bf16_f32 %0, %1, %2" : "=v"(r) : "v"(lo), "v"(hi)); return r; }
; DI int v_st(int k, int c) { const int kk = (k & ~0xC) | ((k & 4) << 1) | ((k & 8) >> 1); return ((kk >> 3) * 4 + (c >> 5)) * 512 + ((kk & 7) * 32 + (c & 31)) * 2; }
; DI int v_rd_base(int lane) { return ((lane & 3) << 3) | (((lane >> 2) & 3) << 6) | (((lane >> 4) & 1) << 5) | (((lane >> 5) & 1) << 8); }
; #define SLOAD(i, k0) do { sr_[i].vs0 = ld8(&Vh[(long)((k0) + sr) * LDK + sc]); sr_[i].vs1 = ld8(&Vh[(long)((k0) + 32 + sr) * LDK + sc]); \
;     sr_[i].ks0 = ld8(&Kh[(long)((k0) + sr) * LDK + sc]); sr_[i].ks1 = ld8(&Kh[(long)((k0) + 32 + sr) * LDK + sc]); } while (0)
; #define SWRITE(b, i) do { *(bf16x8*)((char*)V_lds + (b) * SHM_V + vst0) = sr_[i].vs0;          \
;     *(bf16x8*)((char*)V_lds + (b) * SHM_V + vst1) = sr_[i].vs1; int kc = sc * 2;               \
;     *(bf16x8*)((char*)K_lds + (b) * SHM_K + KSWZ(sr, kc)) = sr_[i].ks0;                       \
;     *(bf16x8*)((char*)K_lds + (b) * SHM_K + KSWZ(32 + sr, kc)) = sr_[i].ks1; } while (0)
; DI void attn_dense_body(const bf16_t* __restrict__ Qb, const bf16_t* __restrict__ Kh, const bf16_t* __restrict__ Vh, ...
;     ...
;     for (int d0 = 0; d0 < 8; ++d0) { u32x4 w = {cvtpk(xf[d0][0], xf[d0][1]), cvtpk(xf[d0][2], xf[d0][3]), cvtpk(xf[d0][4], xf[d0][5]), cvtpk(xf[d0][6], xf[d0][7])}; qr[d0] = *reinterpret_cast<bf16x8*>(&w); }
;   }
;   const int sr = tid >> 4, sc = (tid & 15) * 8, vst0 = v_st(sr, sc), vst1 = v_st(32 + sr, sc);
;   const int vb0 = (int)(uintptr_t)V_lds + v_rd_base(lane);
;   struct { bf16x8 vs0, vs1, ks0, ks1; } sr_[2];
;     ...
;   f32x16 pA0, pA1, pB0, pB1; float mnA, mnB, alA, alB; bf16x8 pa0, pa1, pa2, pa3; const int NT = seq / KVBLK;
;   constexpr int SE = 0, SO = 1;
;   SLOAD(SE, 0); asm volatile("s_waitcnt vmcnt(0)" ::: "memory"); SWRITE(0, SE); __syncthreads();
;   qkt(pA0, pA1, K_lds, qr, r32, hi); partialSM(pA0, pA1, m_reg, mnA, alA);
.LBB0_834:
	s_or_b32 s4, s0, s12
	s_mov_b32 s5, s1
	s_lshl_b64 s[10:11], s[4:5], 1
	v_ashrrev_i32_e32 v176, 4, v160
	s_add_u32 s4, s96, s10
	v_cvt_pk_bf16_f32 v116, v114, v113
	v_cvt_pk_bf16_f32 v117, v106, v105
	v_cvt_pk_bf16_f32 v118, v98, v55
	v_cvt_pk_bf16_f32 v119, v90, v65
	v_cvt_pk_bf16_f32 v124, v88, v67
	v_cvt_pk_bf16_f32 v125, v86, v73
	v_cvt_pk_bf16_f32 v126, v84, v79
	v_cvt_pk_bf16_f32 v127, v82, v81
	v_cvt_pk_bf16_f32 v120, v40, v41
	v_cvt_pk_bf16_f32 v121, v42, v43
	v_cvt_pk_bf16_f32 v122, v44, v45
	v_cvt_pk_bf16_f32 v123, v46, v47
	v_cvt_pk_bf16_f32 v112, v56, v57
	v_cvt_pk_bf16_f32 v113, v58, v59
	v_cvt_pk_bf16_f32 v114, v60, v61
	v_cvt_pk_bf16_f32 v115, v62, v63
	v_cvt_pk_bf16_f32 v108, v76, v77
	v_cvt_pk_bf16_f32 v109, v74, v75
	v_cvt_pk_bf16_f32 v110, v70, v71
	v_cvt_pk_bf16_f32 v111, v68, v69
	v_cvt_pk_bf16_f32 v104, v38, v39
	v_cvt_pk_bf16_f32 v105, v36, v37
	v_cvt_pk_bf16_f32 v106, v34, v35
	v_cvt_pk_bf16_f32 v107, v32, v33
	v_cvt_pk_bf16_f32 v100, v28, v29
	v_cvt_pk_bf16_f32 v101, v30, v31
	v_cvt_pk_bf16_f32 v102, v18, v19
	v_cvt_pk_bf16_f32 v103, v20, v21
	v_cvt_pk_bf16_f32 v96, v22, v23
	v_cvt_pk_bf16_f32 v97, v26, v27
	v_cvt_pk_bf16_f32 v98, v16, v17
	v_lshlrev_b32_e32 v16, 3, v160
	v_add_u32_e32 v184, 32, v176
	s_addc_u32 s5, s97, s11
	v_readlane_b32 s13, v254, 38
	v_and_b32_e32 v178, 0x78, v16
	v_ashrrev_i32_e32 v177, 31, v176
	v_ashrrev_i32_e32 v185, 31, v184
	s_add_u32 s10, s13, s10
	v_readlane_b32 s13, v254, 39
	v_lshlrev_b32_e32 v72, 1, v178
	v_lshlrev_b64 v[48:49], 9, v[176:177]
	v_lshlrev_b64 v[12:13], 9, v[184:185]
	s_addc_u32 s11, s13, s11
	v_or_b32_e32 v8, v48, v72
	v_mov_b32_e32 v9, v49
	v_or_b32_e32 v12, v12, v72
	v_lshl_add_u64 v[0:1], s[10:11], 0, v[8:9]
	v_lshl_add_u64 v[4:5], s[10:11], 0, v[12:13]
	v_cvt_pk_bf16_f32 v99, v24, v25
	global_load_dwordx4 v[0:3], v[0:1], off
	s_nop 0
	global_load_dwordx4 v[4:7], v[4:5], off
	v_lshl_add_u64 v[8:9], s[4:5], 0, v[8:9]
	global_load_dwordx4 v[8:11], v[8:9], off
	v_lshl_add_u64 v[12:13], s[4:5], 0, v[12:13]
	global_load_dwordx4 v[12:15], v[12:13], off
	v_and_b32_e32 v18, 0xfffff0, v176
	v_lshlrev_b32_e32 v19, 1, v176
	v_lshrrev_b32_e32 v20, 1, v176
	v_and_b32_e32 v21, 3, v176
	v_and_or_b32 v18, v19, 8, v18
	v_and_or_b32 v19, v20, 4, v21
	v_and_b32_e32 v20, 0xfffff0, v184
	v_lshlrev_b32_e32 v21, 1, v184
	v_bfe_u32 v16, v16, 5, 2
	v_lshrrev_b32_e32 v18, 1, v18
	v_and_or_b32 v20, v21, 8, v20
	v_or_b32_e32 v18, v18, v16
	v_lshrrev_b32_e32 v20, 1, v20
	v_lshlrev_b32_e32 v19, 6, v19
	v_and_b32_e32 v23, 48, v72
	v_lshlrev_b32_e32 v18, 9, v18
	v_or_b32_e32 v16, v20, v16
	v_and_b32_e32 v17, 0x70, v160
	v_lshlrev_b32_e32 v22, 8, v176
	v_or3_b32 v18, v18, v19, v23
	v_lshlrev_b32_e32 v16, 9, v16
	v_bitop3_b32 v21, v72, v22, v17 bitop3:0xde
	v_or3_b32 v16, v16, v19, v23
	v_add_u32_e32 v204, 0, v18
	v_add_u32_e32 v203, 0, v21
	s_waitcnt vmcnt(0)
	v_add_u32_e32 v205, 0, v16
	s_waitcnt vmcnt(3)
	ds_write_b128 v204, v[0:3]
	s_waitcnt vmcnt(2)
	ds_write_b128 v205, v[4:7]
	s_waitcnt vmcnt(1)
	ds_write_b128 v203, v[8:11] offset:32768
	v_lshlrev_b32_e32 v0, 8, v184
	v_bitop3_b32 v0, v72, v0, v17 bitop3:0xde
	v_add_u32_e32 v206, 0, v0
	v_lshlrev_b32_e32 v0, 4, v196
	v_lshlrev_b32_e32 v66, 8, v196
	v_and_b32_e32 v67, 0x70, v0
	v_bitop3_b32 v0, v180, v66, v67 bitop3:0xde
	v_add_u32_e32 v207, 0, v0
	s_waitcnt vmcnt(0)
	ds_write_b128 v206, v[12:15] offset:32768
	s_waitcnt lgkmcnt(0)
	s_barrier
	ds_read_b128 v[0:3], v207 offset:32768
	ds_read_b128 v[4:7], v207 offset:40960
	s_waitcnt lgkmcnt(1)
	v_mfma_f32_32x32x16_bf16 v[16:31], v[0:3], v[116:119], 0
	v_or_b32_e32 v0, 32, v180
	v_bitop3_b32 v0, v0, v66, v67 bitop3:0xde
	v_add_u32_e32 v210, 0, v0
	s_add_i32 s13, 0, 0x10000
	v_and_b32_e32 v74, 63, v160
	v_lshlrev_b32_e32 v68, 3, v74
	v_add_u32_e32 v186, 64, v176
	s_waitcnt lgkmcnt(0)
	v_mfma_f32_32x32x16_bf16 v[32:47], v[4:7], v[116:119], 0
	ds_read_b128 v[0:3], v210 offset:32768
	ds_read_b128 v[4:7], v210 offset:40960
	v_ashrrev_i32_e32 v187, 31, v186
	v_add_u32_e32 v188, 0x60, v176
	v_lshlrev_b64 v[8:9], 9, v[186:187]
	v_ashrrev_i32_e32 v189, 31, v188
	v_lshlrev_b32_e32 v70, 1, v74
	v_or_b32_e32 v8, v8, v72
	s_waitcnt lgkmcnt(1)
	v_mfma_f32_32x32x16_bf16 v[16:31], v[0:3], v[124:127], v[16:31]
	v_or_b32_e32 v0, 64, v180
	v_bitop3_b32 v0, v0, v66, v67 bitop3:0xde
	v_add_u32_e32 v211, 0, v0
	v_lshlrev_b64 v[12:13], 9, v[188:189]
	v_lshl_add_u64 v[10:11], s[10:11], 0, v[8:9]
	v_or_b32_e32 v12, v12, v72
	v_lshl_add_u64 v[8:9], s[4:5], 0, v[8:9]
	s_waitcnt lgkmcnt(0)
	v_mfma_f32_32x32x16_bf16 v[32:47], v[4:7], v[124:127], v[32:47]
	ds_read_b128 v[0:3], v211 offset:32768
	ds_read_b128 v[4:7], v211 offset:40960
	v_lshl_add_u64 v[14:15], s[10:11], 0, v[12:13]
	v_add_u32_e32 v190, 0x80, v176
	v_ashrrev_i32_e32 v191, 31, v190
	v_add_u32_e32 v192, 0xa0, v176
	v_ashrrev_i32_e32 v193, 31, v192
	s_cmp_lg_u32 0, -1
	s_waitcnt lgkmcnt(1)
	v_mfma_f32_32x32x16_bf16 v[16:31], v[0:3], v[120:123], v[16:31]
	v_or_b32_e32 v0, 0x60, v180
	v_bitop3_b32 v0, v0, v66, v67 bitop3:0xde
	v_add_u32_e32 v208, 0, v0
	s_mov_b32 s69, s68
	s_mov_b32 s70, s68
	s_mov_b32 s71, s68
	s_mov_b32 s72, s68
	s_waitcnt lgkmcnt(0)
	v_mfma_f32_32x32x16_bf16 v[32:47], v[4:7], v[120:123], v[32:47]
	ds_read_b128 v[0:3], v208 offset:32768
	ds_read_b128 v[4:7], v208 offset:40960
	s_mov_b32 s73, s68
	s_mov_b32 s74, s68
	s_mov_b32 s75, s68
	s_mov_b32 s76, s68
	s_mov_b32 s77, s68
	s_mov_b32 s78, s68
	s_waitcnt lgkmcnt(1)
	v_mfma_f32_32x32x16_bf16 v[16:31], v[0:3], v[112:115], v[16:31]
	v_or_b32_e32 v0, 0x80, v180
	v_bitop3_b32 v0, v0, v66, v67 bitop3:0xde
	v_add_u32_e32 v209, 0, v0
	ds_read_b128 v[0:3], v209 offset:32768
	s_mov_b32 s79, s68
	s_mov_b32 s80, s68
	s_mov_b32 s81, s68
	s_waitcnt lgkmcnt(1)
; #define SLOAD(i, k0) do { sr_[i].vs0 = ld8(&Vh[(long)((k0) + sr) * LDK + sc]); sr_[i].vs1 = ld8(&Vh[(long)((k0) + 32 + sr) * LDK + sc]); \
;     sr_[i].ks0 = ld8(&Kh[(long)((k0) + sr) * LDK + sc]); sr_[i].ks1 = ld8(&Kh[(long)((k0) + 32 + sr) * LDK + sc]); } while (0)
; #define SWRITE(b, i) do { *(bf16x8*)((char*)V_lds + (b) * SHM_V + vst0) = sr_[i].vs0;          \
;     *(bf16x8*)((char*)V_lds + (b) * SHM_V + vst1) = sr_[i].vs1; int kc = sc * 2;               \
;     *(bf16x8*)((char*)K_lds + (b) * SHM_K + KSWZ(sr, kc)) = sr_[i].ks0;                       \
;     *(bf16x8*)((char*)K_lds + (b) * SHM_K + KSWZ(32 + sr, kc)) = sr_[i].ks1; } while (0)
; #define SWAIT() asm volatile("s_waitcnt vmcnt(4)" ::: "memory")
; DI void partialSM(f32x16& p0, f32x16& p1, float& m_reg, float& mn, float& alpha) {
;   constexpr float C = SCALE * 1.4426950408889634f;
;   float pmax = p0[0]; for (int r = 1; r < 16; ++r) pmax = fmaxf(pmax, p0[r]); for (int r = 0; r < 16; ++r) pmax = fmaxf(pmax, p1[r]);
;   { auto rr = __builtin_amdgcn_permlane32_swap(__float_as_uint(pmax), __float_as_uint(pmax), false, false);
;     pmax = fmaxf(__uint_as_float(rr[0]), __uint_as_float(rr[1])); }
;   if (__builtin_expect(__all(pmax - m_reg <= THR / SCALE), 1)) { mn = m_reg; alpha = 1.f; }
;   else { mn = fmaxf(m_reg, pmax); alpha = __builtin_amdgcn_exp2f((m_reg - mn) * C); m_reg = mn; }
;   float mnC = -mn * C;
;   for (int r = 0; r < 16; ++r) p0[r] = fmaf(p0[r], C, mnC); for (int r = 0; r < 16; ++r) p1[r] = fmaf(p1[r], C, mnC);
;   for (int r = 0; r < 16; ++r) p0[r] = __builtin_amdgcn_exp2f(p0[r]);
; }
; DI void attn_dense_body(const bf16_t* __restrict__ Qb, const bf16_t* __restrict__ Kh, const bf16_t* __restrict__ Vh, ...
;     ...
;   f32x16 pA0, pA1, pB0, pB1; float mnA, mnB, alA, alB; bf16x8 pa0, pa1, pa2, pa3; const int NT = seq / KVBLK;
;   constexpr int SE = 0, SO = 1;
;   SLOAD(SE, 0); asm volatile("s_waitcnt vmcnt(0)" ::: "memory"); SWRITE(0, SE); __syncthreads();
;   qkt(pA0, pA1, K_lds, qr, r32, hi); partialSM(pA0, pA1, m_reg, mnA, alA);
;   SLOAD(SO, KVBLK); if (2 < NT) SLOAD(SE, 2 * KVBLK);
;   SWAIT(); SWRITE(1, SO); __syncthreads();
	v_mfma_f32_32x32x16_bf16 v[32:47], v[4:7], v[112:115], v[32:47]
	ds_read_b128 v[4:7], v209 offset:40960
	s_mov_b32 s82, s68
	s_mov_b32 s83, s68
	s_mov_b32 s16, 4
	v_mov_b32_e32 v200, 0
	s_waitcnt lgkmcnt(1)
	v_mfma_f32_32x32x16_bf16 v[16:31], v[0:3], v[108:111], v[16:31]
	v_and_b32_e32 v0, 0x3fffffc0, v160
	v_lshl_add_u32 v198, v0, 2, s13
	v_or_b32_e32 v0, 0xa0, v180
	v_bitop3_b32 v0, v0, v66, v67 bitop3:0xde
	v_add_u32_e32 v212, 0, v0
	ds_read_b128 v[0:3], v212 offset:32768
	s_cselect_b32 s13, 0, 0
	s_waitcnt lgkmcnt(1)
	v_mfma_f32_32x32x16_bf16 v[32:47], v[4:7], v[108:111], v[32:47]
	v_lshlrev_b32_e32 v4, 4, v74
	v_and_b32_e32 v4, 0xc0, v4
	v_and_or_b32 v69, v68, 24, v4
	ds_read_b128 v[4:7], v212 offset:40960
	v_lshl_add_u32 v199, v196, 2, v198
	s_waitcnt lgkmcnt(1)
	v_mfma_f32_32x32x16_bf16 v[16:31], v[0:3], v[104:107], v[16:31]
	v_or_b32_e32 v0, 0xc0, v180
	v_bitop3_b32 v0, v0, v66, v67 bitop3:0xde
	v_add_u32_e32 v213, 0, v0
	ds_read_b128 v[0:3], v213 offset:32768
	global_load_dwordx4 v[50:53], v[10:11], off
	global_load_dwordx4 v[54:57], v[14:15], off
	v_lshl_add_u64 v[10:11], s[4:5], 0, v[12:13]
	global_load_dwordx4 v[58:61], v[8:9], off
	global_load_dwordx4 v[62:65], v[10:11], off
	s_waitcnt lgkmcnt(0)
	v_mfma_f32_32x32x16_bf16 v[16:31], v[0:3], v[100:103], v[16:31]
	v_or_b32_e32 v0, 0xe0, v180
	v_bitop3_b32 v0, v0, v66, v67 bitop3:0xde
	v_add_u32_e32 v214, 0, v0
	ds_read_b128 v[0:3], v214 offset:32768
	v_mfma_f32_32x32x16_bf16 v[32:47], v[4:7], v[104:107], v[32:47]
	v_and_b32_e32 v4, 32, v70
	v_and_b32_e32 v5, 0x100, v68
	v_or3_b32 v75, v69, v4, v5
	ds_read_b128 v[4:7], v213 offset:40960
	ds_read_b128 v[66:69], v214 offset:40960
	v_lshlrev_b64 v[70:71], 9, v[192:193]
	v_or_b32_e32 v70, v70, v72
	s_waitcnt lgkmcnt(1)
	v_mfma_f32_32x32x16_bf16 v[32:47], v[4:7], v[100:103], v[32:47]
	v_add_u32_e32 v202, s13, v75
	v_mfma_f32_32x32x16_bf16 v[16:31], v[0:3], v[96:99], v[16:31]
	v_mov_b64_e32 v[0:1], s[68:69]
	v_mov_b64_e32 v[14:15], s[82:83]
	v_mov_b64_e32 v[2:3], s[70:71]
	v_mov_b64_e32 v[4:5], s[72:73]
	v_mov_b64_e32 v[6:7], s[74:75]
	v_mov_b64_e32 v[8:9], s[76:77]
	v_mov_b64_e32 v[10:11], s[78:79]
	s_waitcnt lgkmcnt(0)
	v_mfma_f32_32x32x16_bf16 v[32:47], v[66:69], v[96:99], v[32:47]
	s_nop 2
	v_max_f32_e32 v66, v17, v17
	v_max_f32_e32 v67, v16, v16
	v_max_f32_e32 v66, v67, v66
	v_max3_f32 v66, v66, v18, v19
	v_max3_f32 v66, v66, v20, v21
	v_max3_f32 v66, v66, v22, v23
	v_max3_f32 v66, v66, v24, v25
	v_max3_f32 v66, v66, v26, v27
	v_max3_f32 v66, v66, v28, v29
	v_max3_f32 v66, v66, v30, v31
	v_max3_f32 v66, v66, v32, v33
	v_max3_f32 v66, v66, v34, v35
	v_max3_f32 v66, v66, v36, v37
	v_max3_f32 v66, v66, v38, v39
	v_max3_f32 v66, v66, v40, v41
	v_max3_f32 v66, v66, v42, v43
	v_max3_f32 v66, v66, v44, v45
	v_max3_f32 v76, v66, v46, v47
	v_lshlrev_b64 v[66:67], 9, v[190:191]
	v_or_b32_e32 v66, v66, v72
	v_lshl_add_u64 v[68:69], s[10:11], 0, v[66:67]
	v_lshl_add_u64 v[66:67], s[4:5], 0, v[66:67]
	v_lshl_add_u64 v[72:73], s[10:11], 0, v[70:71]
	global_load_dwordx4 v[128:131], v[68:69], off
	global_load_dwordx4 v[136:139], v[72:73], off
	v_lshl_add_u64 v[68:69], s[4:5], 0, v[70:71]
	global_load_dwordx4 v[132:135], v[66:67], off
	global_load_dwordx4 v[140:143], v[68:69], off
	v_mov_b32_e32 v77, v76
	s_nop 1
	v_permlane32_swap_b32_e32 v76, v77
	v_max_f32_e32 v66, v77, v77
	v_max_f32_e32 v67, v76, v76
	v_max_f32_e32 v66, v67, v66
	s_waitcnt vmcnt(4)
	s_waitcnt vmcnt(7)
	ds_write_b128 v204, v[50:53] offset:16384
	s_waitcnt vmcnt(6)
	ds_write_b128 v205, v[54:57] offset:16384
	s_waitcnt vmcnt(5)
	ds_write_b128 v203, v[58:61] offset:49152
	s_waitcnt vmcnt(4)
	ds_write_b128 v206, v[62:65] offset:49152
	v_max_f32_e32 v50, 0xf149f2ca, v66
	v_sub_f32_e32 v51, 0xf149f2ca, v50
	v_mul_f32_e32 v51, 0x3e0293ee, v51
	v_add_f32_e32 v67, 0x7149f2ca, v66
	v_exp_f32_e32 v51, v51
	v_cmp_ge_f32_e32 vcc, s95, v67
	s_cmp_eq_u64 vcc, exec
	s_cselect_b64 vcc, -1, 0
	v_cndmask_b32_e64 v215, v51, 1.0, vcc
	v_mov_b32_e32 v51, 0xf149f2ca
	v_cndmask_b32_e32 v168, v50, v51, vcc
	v_mul_f32_e32 v50, 0xbe0293ee, v168
	v_fmamk_f32 v16, v16, 0x3e0293ee, v50
	v_exp_f32_e32 v161, v16
	v_fmamk_f32 v16, v17, 0x3e0293ee, v50
	v_exp_f32_e32 v175, v16
	v_fmamk_f32 v16, v18, 0x3e0293ee, v50
	v_exp_f32_e32 v162, v16
	v_fmamk_f32 v16, v19, 0x3e0293ee, v50
	v_exp_f32_e32 v219, v16
	v_fmamk_f32 v16, v20, 0x3e0293ee, v50
	v_exp_f32_e32 v174, v16
	v_fmamk_f32 v16, v21, 0x3e0293ee, v50
	v_exp_f32_e32 v222, v16
	v_fmamk_f32 v16, v22, 0x3e0293ee, v50
	v_exp_f32_e32 v163, v16
	v_fmamk_f32 v16, v23, 0x3e0293ee, v50
	v_exp_f32_e32 v173, v16
	v_fmamk_f32 v16, v24, 0x3e0293ee, v50
	v_exp_f32_e32 v164, v16
	v_fmamk_f32 v16, v25, 0x3e0293ee, v50
	v_exp_f32_e32 v171, v16
	v_fmamk_f32 v16, v26, 0x3e0293ee, v50
	v_exp_f32_e32 v165, v16
	v_fmamk_f32 v16, v27, 0x3e0293ee, v50
	s_addk_i32 s13, 0x4000
	v_exp_f32_e32 v172, v16
	v_fmamk_f32 v16, v28, 0x3e0293ee, v50
	s_add_u32 s0, s0, s12
	v_exp_f32_e32 v166, v16
	v_fmamk_f32 v16, v29, 0x3e0293ee, v50
	s_addc_u32 s1, s1, 0
	v_pk_fma_f32 v[144:145], v[46:47], s[42:43], v[50:51] op_sel_hi:[1,0,0]
	v_pk_fma_f32 v[150:151], v[44:45], s[42:43], v[50:51] op_sel_hi:[1,0,0]
	v_pk_fma_f32 v[154:155], v[42:43], s[42:43], v[50:51] op_sel_hi:[1,0,0]
	v_pk_fma_f32 v[146:147], v[40:41], s[42:43], v[50:51] op_sel_hi:[1,0,0]
	v_pk_fma_f32 v[148:149], v[38:39], s[42:43], v[50:51] op_sel_hi:[1,0,0]
	v_pk_fma_f32 v[152:153], v[36:37], s[42:43], v[50:51] op_sel_hi:[1,0,0]
	v_pk_fma_f32 v[156:157], v[34:35], s[42:43], v[50:51] op_sel_hi:[1,0,0]
	v_pk_fma_f32 v[158:159], v[32:33], s[42:43], v[50:51] op_sel_hi:[1,0,0]
	v_exp_f32_e32 v169, v16
	v_fmamk_f32 v16, v30, 0x3e0293ee, v50
	v_fmac_f32_e32 v50, 0x3e0293ee, v31
	s_lshl_b64 s[0:1], s[0:1], 1
	v_readlane_b32 s10, v255, 31
	v_exp_f32_e32 v167, v16
	v_exp_f32_e32 v170, v50
	v_and_b32_e32 v16, 15, v160
	s_add_u32 s0, s10, s0
	v_readlane_b32 s10, v255, 32
	v_lshl_or_b32 v48, v16, 4, v48
	s_addc_u32 s1, s10, s1
	v_mov_b64_e32 v[12:13], s[80:81]
	v_lshl_add_u64 v[194:195], s[0:1], 0, v[48:49]
	v_mov_b64_e32 v[62:63], v[14:15]
	v_mov_b64_e32 v[46:47], v[14:15]
	v_mov_b64_e32 v[30:31], v[14:15]
	v_cmp_gt_u32_e64 s[4:5], 32, v74
	v_add_u32_e32 v201, s13, v75
	v_mov_b64_e32 v[60:61], v[12:13]
	v_mov_b64_e32 v[58:59], v[10:11]
	v_mov_b64_e32 v[56:57], v[8:9]
	v_mov_b64_e32 v[54:55], v[6:7]
	v_mov_b64_e32 v[52:53], v[4:5]
	v_mov_b64_e32 v[50:51], v[2:3]
	v_mov_b64_e32 v[48:49], v[0:1]
	v_mov_b64_e32 v[44:45], v[12:13]
	v_mov_b64_e32 v[42:43], v[10:11]
	v_mov_b64_e32 v[40:41], v[8:9]
	v_mov_b64_e32 v[38:39], v[6:7]
	v_mov_b64_e32 v[36:37], v[4:5]
	v_mov_b64_e32 v[34:35], v[2:3]
	v_mov_b64_e32 v[32:33], v[0:1]
	v_mov_b64_e32 v[28:29], v[12:13]
	v_mov_b64_e32 v[26:27], v[10:11]
	v_mov_b64_e32 v[24:25], v[8:9]
	v_mov_b64_e32 v[22:23], v[6:7]
	v_mov_b64_e32 v[20:21], v[4:5]
	v_mov_b64_e32 v[18:19], v[2:3]
	v_mov_b64_e32 v[16:17], v[0:1]
	v_readfirstlane_b32 s100, v252
	s_nop 3
	s_lshr_b32 s100, s100, 6
	s_cmp_ge_u32 s100, 4
	s_cbranch_scc0 .Lattn_prio_done
	s_setprio 1
.Lattn_prio_done:
	s_waitcnt lgkmcnt(0)
	s_barrier

; __global__ void __launch_bounds__(NTHREADS, 2) fwd_megakernel(Args a) {
	.amdhsa_kernel _Z14fwd_megakernel4Args
		.amdhsa_group_segment_fixed_size 0
		.amdhsa_private_segment_fixed_size 0
		.amdhsa_kernarg_size 408
		.amdhsa_user_sgpr_count 2
		.amdhsa_user_sgpr_dispatch_ptr 0
		.amdhsa_user_sgpr_queue_ptr 0
		.amdhsa_user_sgpr_kernarg_segment_ptr 1
		.amdhsa_user_sgpr_dispatch_id 0
		.amdhsa_user_sgpr_kernarg_preload_length 0
		.amdhsa_user_sgpr_kernarg_preload_offset 0
		.amdhsa_user_sgpr_private_segment_size 0
		.amdhsa_uses_dynamic_stack 0
		.amdhsa_enable_private_segment 0
		.amdhsa_system_sgpr_workgroup_id_x 1
		.amdhsa_system_sgpr_workgroup_id_y 0
		.amdhsa_system_sgpr_workgroup_id_z 0
		.amdhsa_system_sgpr_workgroup_info 0
		.amdhsa_system_vgpr_workitem_id 2
		.amdhsa_next_free_vgpr 256
		.amdhsa_next_free_sgpr 102
		.amdhsa_accum_offset 256
		.amdhsa_reserve_vcc 1
		.amdhsa_float_round_mode_32 0
		.amdhsa_float_round_mode_16_64 0
		.amdhsa_float_denorm_mode_32 3
		.amdhsa_float_denorm_mode_16_64 3
		.amdhsa_dx10_clamp 1
		.amdhsa_ieee_mode 1
		.amdhsa_fp16_overflow 0
		.amdhsa_tg_split 0
		.amdhsa_exception_fp_ieee_invalid_op 0
		.amdhsa_exception_fp_denorm_src 0
		.amdhsa_exception_fp_ieee_div_zero 0
		.amdhsa_exception_fp_ieee_overflow 0
		.amdhsa_exception_fp_ieee_underflow 0
		.amdhsa_exception_fp_ieee_inexact 0
		.amdhsa_exception_int_div_zero 0
	.end_amdhsa_kernel

; __global__ void __launch_bounds__(NTHREADS, 2) fwd_megakernel(Args a) {
amdhsa.kernels:
  - .agpr_count:     0
    .args:
      - .offset:         0
        .size:           152
        .value_kind:     by_value
      - .offset:         152
        .size:           4
        .value_kind:     hidden_block_count_x
      - .offset:         156
        .size:           4
        .value_kind:     hidden_block_count_y
      - .offset:         160
        .size:           4
        .value_kind:     hidden_block_count_z
      - .offset:         164
        .size:           2
        .value_kind:     hidden_group_size_x
      - .offset:         166
        .size:           2
        .value_kind:     hidden_group_size_y
      - .offset:         168
        .size:           2
        .value_kind:     hidden_group_size_z
      - .offset:         170
        .size:           2
        .value_kind:     hidden_remainder_x
      - .offset:         172
        .size:           2
        .value_kind:     hidden_remainder_y
      - .offset:         174
        .size:           2
        .value_kind:     hidden_remainder_z
      - .offset:         192
        .size:           8
        .value_kind:     hidden_global_offset_x
      - .offset:         200
        .size:           8
        .value_kind:     hidden_global_offset_y
      - .offset:         208
        .size:           8
        .value_kind:     hidden_global_offset_z
      - .offset:         216
        .size:           2
        .value_kind:     hidden_grid_dims
      - .offset:         240
        .size:           8
        .value_kind:     hidden_multigrid_sync_arg
      - .offset:         272
        .size:           4
        .value_kind:     hidden_dynamic_lds_size
    .group_segment_fixed_size: 0
    .kernarg_segment_align: 8
    .kernarg_segment_size: 408
    .language:       OpenCL C
    .language_version:
      - 2
      - 0
    .max_flat_workgroup_size: 512
    .name:           _Z14fwd_megakernel4Args
    .private_segment_fixed_size: 0
    .sgpr_count:     108
    .sgpr_spill_count: 194
    .symbol:         _Z14fwd_megakernel4Args.kd
    .uniform_work_group_size: 1
    .uses_dynamic_stack: false
    .vgpr_count:     256
    .vgpr_spill_count: 0
    .wavefront_size: 64
